# v20: v16 plus MoBA own-block bit folded into the per-lane select mask so the keep mask needs no scalar OR between the vector compare and the selects
# baseline (speedup 1.0000x reference)
; __device__ __forceinline__ float bflo(unsigned w) { return __uint_as_float(w << 16); }
; __device__ __forceinline__ float bfhi(unsigned w) { return __uint_as_float(w & 0xffff0000u); }
; __global__ void __launch_bounds__(NWAVES * 64, 2) mega_fwd(Args args) {
;     ...
;                 for (int d0 = 0; d0 < 128; d0 += 8) {
;                     const v4u qw4 = *(const v4u*)(qrow + d0);
;                     const float q8[8] = {bflo(qw4.x), bfhi(qw4.x), bflo(qw4.y), bfhi(qw4.y), bflo(qw4.z), bfhi(qw4.z), bflo(qw4.w), bfhi(qw4.w)};
; #pragma unroll
;                     for (int j = 0; j < 8; ++j) { const f32x4 k0 = *(const f32x4*)(km + j * 128 + d0), k1 = *(const f32x4*)(km + j * 128 + d0 + 4);
;                         g8[j] += q8[0] * k0.x + q8[1] * k0.y + q8[2] * k0.z + q8[3] * k0.w + q8[4] * k1.x + q8[5] * k1.y + q8[6] * k1.z + q8[7] * k1.w; }
;                 }
.LBB0_132:
	v_lshl_add_u64 v[18:19], s[72:73], 0, v[6:7]
	v_lshl_add_u64 v[22:23], v[18:19], 0, s[62:63]
	v_add_co_u32_e32 v18, vcc, s10, v18
	s_waitcnt vmcnt(17)
	v_lshl_add_u64 v[134:135], s[72:73], 0, v[4:5]
	v_addc_co_u32_e32 v19, vcc, 0, v19, vcc
	global_load_dwordx4 v[18:21], v[18:19], off offset:1664
	s_nop 0
	global_load_dwordx4 v[22:25], v[22:23], off offset:16
	s_mov_b32 s8, 0x400000
	v_add_co_u32_e32 v136, vcc, s8, v134
	s_mov_b64 s[8:9], 0x400200
	v_lshl_add_u64 v[34:35], v[134:135], 0, s[12:13]
	v_addc_co_u32_e32 v137, vcc, 0, v135, vcc
	v_lshl_add_u64 v[50:51], v[134:135], 0, s[8:9]
	s_mov_b64 s[8:9], 0x400400
	v_lshl_add_u64 v[66:67], v[134:135], 0, s[8:9]
	s_mov_b64 s[8:9], 0x400600
	v_lshl_add_u64 v[82:83], v[134:135], 0, s[8:9]
	s_mov_b64 s[8:9], 0x400800
	v_lshl_add_u64 v[98:99], v[134:135], 0, s[8:9]
	s_mov_b64 s[8:9], 0x400a00
	v_lshl_add_u64 v[114:115], v[134:135], 0, s[8:9]
	s_mov_b64 s[8:9], 0x400c00
	v_lshl_add_u64 v[130:131], v[134:135], 0, s[8:9]
	s_mov_b64 s[8:9], 0x400e00
	v_lshl_add_u64 v[146:147], v[134:135], 0, s[8:9]
	s_add_i32 s7, s7, 16
	v_lshl_add_u64 v[4:5], v[4:5], 0, 64
	v_lshl_add_u64 v[6:7], v[6:7], 0, 32
	s_cmpk_gt_u32 s7, 0x77
	s_waitcnt vmcnt(1)
	v_lshlrev_b32_e32 v150, 16, v18
	v_and_b32_e32 v151, 0xffff0000, v18
	v_lshlrev_b32_e32 v0, 16, v19
	v_and_b32_e32 v152, 0xffff0000, v19
	v_lshlrev_b32_e32 v154, 16, v20
	v_and_b32_e32 v156, 0xffff0000, v20
	v_lshlrev_b32_e32 v158, 16, v21
	v_and_b32_e32 v160, 0xffff0000, v21
	global_load_dwordx4 v[18:21], v[136:137], off
	global_load_dwordx4 v[26:29], v[34:35], off offset:32
	global_load_dwordx4 v[30:33], v[34:35], off offset:48
	s_nop 0
	global_load_dwordx4 v[34:37], v[34:35], off offset:16
	s_nop 0
	global_load_dwordx4 v[38:41], v[136:137], off offset:512
	global_load_dwordx4 v[42:45], v[50:51], off offset:32
	global_load_dwordx4 v[46:49], v[50:51], off offset:48
	s_nop 0
	global_load_dwordx4 v[50:53], v[50:51], off offset:16
	s_nop 0
	global_load_dwordx4 v[54:57], v[136:137], off offset:1024
	global_load_dwordx4 v[58:61], v[66:67], off offset:32
	global_load_dwordx4 v[62:65], v[66:67], off offset:48
	s_nop 0
	global_load_dwordx4 v[66:69], v[66:67], off offset:16
	s_nop 0
	global_load_dwordx4 v[70:73], v[136:137], off offset:1536
	global_load_dwordx4 v[74:77], v[82:83], off offset:32
	global_load_dwordx4 v[78:81], v[82:83], off offset:48
	s_nop 0
	global_load_dwordx4 v[82:85], v[82:83], off offset:16
	s_nop 0
	global_load_dwordx4 v[86:89], v[136:137], off offset:2048
	global_load_dwordx4 v[90:93], v[98:99], off offset:32
	global_load_dwordx4 v[94:97], v[98:99], off offset:48
	s_nop 0
	global_load_dwordx4 v[98:101], v[98:99], off offset:16
	s_nop 0
	global_load_dwordx4 v[102:105], v[136:137], off offset:2560
	global_load_dwordx4 v[106:109], v[114:115], off offset:32
	global_load_dwordx4 v[110:113], v[114:115], off offset:48
	s_nop 0
	global_load_dwordx4 v[114:117], v[114:115], off offset:16
	s_nop 0
	global_load_dwordx4 v[118:121], v[136:137], off offset:3072
	global_load_dwordx4 v[122:125], v[130:131], off offset:48
	global_load_dwordx4 v[126:129], v[130:131], off offset:32
	s_nop 0
	global_load_dwordx4 v[130:133], v[130:131], off offset:16
	s_nop 0
	global_load_dwordx4 v[134:137], v[136:137], off offset:3584
	s_nop 0
	global_load_dwordx4 v[138:141], v[146:147], off offset:48
	global_load_dwordx4 v[142:145], v[146:147], off offset:32
	s_nop 0
	global_load_dwordx4 v[146:149], v[146:147], off offset:16
	s_waitcnt vmcnt(31)
	v_mov_b32_e32 v163, v20
	s_waitcnt vmcnt(27)
	v_mov_b32_e32 v162, v40
	v_mov_b32_e32 v20, v41
	v_mov_b32_e32 v41, v34
	s_waitcnt vmcnt(24)
	v_mov_b32_e32 v40, v50
	v_mov_b32_e32 v34, v51
	v_mov_b32_e32 v50, v52
	v_mov_b32_e32 v51, v36
	v_mov_b32_e32 v36, v53
	v_mov_b32_e32 v52, v38
	v_mov_b32_e32 v53, v19
	v_pk_mul_f32 v[52:53], v[52:53], v[150:151]
	v_pk_mov_b32 v[18:19], v[38:39], v[18:19] op_sel:[1,0]
	s_waitcnt vmcnt(19)
	v_pk_mov_b32 v[38:39], v[70:71], v[54:55] op_sel:[1,0]
	v_pk_fma_f32 v[18:19], v[18:19], v[150:151], v[52:53] op_sel:[0,1,0] op_sel_hi:[1,0,1]
	s_nop 0
	v_pk_fma_f32 v[18:19], v[162:163], v[0:1], v[18:19] op_sel_hi:[1,0,1]
	s_nop 0
	v_pk_fma_f32 v[18:19], v[20:21], v[152:153], v[18:19] op_sel_hi:[1,0,1]
	s_waitcnt vmcnt(16)
	v_mov_b32_e32 v20, v82
	v_pk_fma_f32 v[18:19], v[40:41], v[154:155], v[18:19] op_sel_hi:[1,0,1]
	v_mov_b32_e32 v21, v66
	v_pk_fma_f32 v[18:19], v[34:35], v[156:157], v[18:19] op_sel_hi:[1,0,1]
	v_mov_b32_e32 v66, v83
	v_pk_fma_f32 v[18:19], v[50:51], v[158:159], v[18:19] op_sel_hi:[1,0,1]
	v_mov_b32_e32 v34, v84
	v_pk_fma_f32 v[18:19], v[36:37], v[160:161], v[18:19] op_sel_hi:[1,0,1]
	v_mov_b32_e32 v36, v70
	v_mov_b32_e32 v37, v55
	v_pk_mul_f32 v[36:37], v[36:37], v[150:151]
	v_pk_add_f32 v[14:15], v[14:15], v[18:19]
	v_mov_b32_e32 v18, v72
	v_mov_b32_e32 v19, v56
	v_pk_fma_f32 v[36:37], v[38:39], v[150:151], v[36:37] op_sel:[0,1,0] op_sel_hi:[1,0,1]
	v_mov_b32_e32 v56, v73
	v_pk_fma_f32 v[18:19], v[18:19], v[0:1], v[36:37] op_sel_hi:[1,0,1]
	v_mov_b32_e32 v35, v68
	v_pk_fma_f32 v[18:19], v[56:57], v[152:153], v[18:19] op_sel_hi:[1,0,1]
	v_mov_b32_e32 v68, v85
	v_pk_fma_f32 v[18:19], v[20:21], v[154:155], v[18:19] op_sel_hi:[1,0,1]
	s_waitcnt vmcnt(11)
	v_mov_b32_e32 v36, v102
	v_pk_fma_f32 v[18:19], v[66:67], v[156:157], v[18:19] op_sel_hi:[1,0,1]
	v_mov_b32_e32 v37, v87
	v_pk_fma_f32 v[18:19], v[34:35], v[158:159], v[18:19] op_sel_hi:[1,0,1]
	v_pk_mul_f32 v[36:37], v[36:37], v[150:151]
	v_pk_fma_f32 v[18:19], v[68:69], v[160:161], v[18:19] op_sel_hi:[1,0,1]
	v_pk_mov_b32 v[38:39], v[102:103], v[86:87] op_sel:[1,0]
	v_pk_add_f32 v[12:13], v[12:13], v[18:19]
	v_mov_b32_e32 v18, v104
	v_mov_b32_e32 v19, v88
	v_pk_fma_f32 v[36:37], v[38:39], v[150:151], v[36:37] op_sel:[0,1,0] op_sel_hi:[1,0,1]
	v_mov_b32_e32 v88, v105
	v_pk_fma_f32 v[18:19], v[18:19], v[0:1], v[36:37] op_sel_hi:[1,0,1]
	s_waitcnt vmcnt(8)
; __device__ __forceinline__ float bflo(unsigned w) { return __uint_as_float(w << 16); }
; __device__ __forceinline__ float bfhi(unsigned w) { return __uint_as_float(w & 0xffff0000u); }
; __global__ void __launch_bounds__(NWAVES * 64, 2) mega_fwd(Args args) {
;     ...
;                 for (int d0 = 0; d0 < 128; d0 += 8) {
;                     const v4u qw4 = *(const v4u*)(qrow + d0);
;                     const float q8[8] = {bflo(qw4.x), bfhi(qw4.x), bflo(qw4.y), bfhi(qw4.y), bflo(qw4.z), bfhi(qw4.z), bflo(qw4.w), bfhi(qw4.w)};
; #pragma unroll
;                     for (int j = 0; j < 8; ++j) { const f32x4 k0 = *(const f32x4*)(km + j * 128 + d0), k1 = *(const f32x4*)(km + j * 128 + d0 + 4);
;                         g8[j] += q8[0] * k0.x + q8[1] * k0.y + q8[2] * k0.z + q8[3] * k0.w + q8[4] * k1.x + q8[5] * k1.y + q8[6] * k1.z + q8[7] * k1.w; }
;                 }
	v_mov_b32_e32 v20, v114
	v_mov_b32_e32 v21, v98
	v_pk_fma_f32 v[18:19], v[88:89], v[152:153], v[18:19] op_sel_hi:[1,0,1]
	v_mov_b32_e32 v98, v115
	v_pk_fma_f32 v[18:19], v[20:21], v[154:155], v[18:19] op_sel_hi:[1,0,1]
	v_mov_b32_e32 v34, v116
	v_mov_b32_e32 v35, v100
	v_pk_fma_f32 v[18:19], v[98:99], v[156:157], v[18:19] op_sel_hi:[1,0,1]
	v_mov_b32_e32 v100, v117
	v_pk_fma_f32 v[18:19], v[34:35], v[158:159], v[18:19] op_sel_hi:[1,0,1]
	s_waitcnt vmcnt(7)
	v_mov_b32_e32 v20, v120
	v_pk_fma_f32 v[18:19], v[100:101], v[160:161], v[18:19] op_sel_hi:[1,0,1]
	s_waitcnt vmcnt(3)
	v_mov_b32_e32 v21, v136
	v_pk_add_f32 v[10:11], v[10:11], v[18:19]
	v_pk_mov_b32 v[18:19], v[118:119], v[134:135] op_sel:[1,0]
	v_mov_b32_e32 v119, v135
	v_pk_mul_f32 v[18:19], v[18:19], v[150:151] op_sel:[0,1] op_sel_hi:[1,0]
	v_mov_b32_e32 v136, v121
	v_pk_fma_f32 v[18:19], v[118:119], v[150:151], v[18:19]
	v_mov_b32_e32 v40, v46
	v_pk_fma_f32 v[18:19], v[20:21], v[0:1], v[18:19] op_sel_hi:[1,0,1]
	v_mov_b32_e32 v20, v130
	v_pk_fma_f32 v[18:19], v[136:137], v[152:153], v[18:19] op_sel_hi:[1,0,1]
	s_waitcnt vmcnt(0)
	v_mov_b32_e32 v21, v146
	v_pk_fma_f32 v[18:19], v[20:21], v[154:155], v[18:19] op_sel_hi:[1,0,1]
	v_mov_b32_e32 v146, v131
	v_pk_fma_f32 v[18:19], v[146:147], v[156:157], v[18:19] op_sel_hi:[1,0,1]
	v_mov_b32_e32 v20, v132
	v_mov_b32_e32 v21, v148
	v_pk_fma_f32 v[18:19], v[20:21], v[158:159], v[18:19] op_sel_hi:[1,0,1]
	v_mov_b32_e32 v148, v133
	v_pk_fma_f32 v[18:19], v[148:149], v[160:161], v[18:19] op_sel_hi:[1,0,1]
	v_mov_b32_e32 v41, v30
	v_pk_add_f32 v[8:9], v[8:9], v[18:19]
	v_lshlrev_b32_e32 v18, 16, v22
	v_and_b32_e32 v19, 0xffff0000, v22
	v_mov_b32_e32 v30, v47
	v_mov_b32_e32 v46, v42
	v_mov_b32_e32 v47, v27
	v_pk_mul_f32 v[46:47], v[46:47], v[18:19]
	v_pk_mov_b32 v[26:27], v[42:43], v[26:27] op_sel:[1,0]
	v_lshlrev_b32_e32 v0, 16, v23
	v_mov_b32_e32 v38, v44
	v_mov_b32_e32 v39, v28
	v_pk_fma_f32 v[26:27], v[26:27], v[18:19], v[46:47] op_sel:[0,1,0] op_sel_hi:[1,0,1]
	v_and_b32_e32 v20, 0xffff0000, v23
	v_mov_b32_e32 v28, v45
	v_pk_fma_f32 v[26:27], v[38:39], v[0:1], v[26:27] op_sel_hi:[1,0,1]
	v_lshlrev_b32_e32 v22, 16, v24
	v_pk_fma_f32 v[26:27], v[28:29], v[20:21], v[26:27] op_sel_hi:[1,0,1]
	v_and_b32_e32 v24, 0xffff0000, v24
	v_pk_fma_f32 v[26:27], v[40:41], v[22:23], v[26:27] op_sel_hi:[1,0,1]
	v_lshlrev_b32_e32 v34, 16, v25
	v_mov_b32_e32 v44, v48
	v_mov_b32_e32 v45, v32
	v_pk_fma_f32 v[26:27], v[30:31], v[24:25], v[26:27] op_sel_hi:[1,0,1]
	v_and_b32_e32 v36, 0xffff0000, v25
	v_mov_b32_e32 v32, v49
	v_pk_fma_f32 v[26:27], v[44:45], v[34:35], v[26:27] op_sel_hi:[1,0,1]
	v_pk_mov_b32 v[38:39], v[74:75], v[58:59] op_sel:[1,0]
	v_pk_fma_f32 v[26:27], v[32:33], v[36:37], v[26:27] op_sel_hi:[1,0,1]
	v_mov_b32_e32 v32, v74
	v_mov_b32_e32 v33, v59
	v_pk_mul_f32 v[32:33], v[32:33], v[18:19]
	v_pk_add_f32 v[14:15], v[14:15], v[26:27]
	v_mov_b32_e32 v26, v76
	v_mov_b32_e32 v27, v60
	v_pk_fma_f32 v[32:33], v[38:39], v[18:19], v[32:33] op_sel:[0,1,0] op_sel_hi:[1,0,1]
	v_mov_b32_e32 v60, v77
	v_pk_fma_f32 v[26:27], v[26:27], v[0:1], v[32:33] op_sel_hi:[1,0,1]
	v_mov_b32_e32 v28, v78
	v_mov_b32_e32 v29, v62
	v_pk_fma_f32 v[26:27], v[60:61], v[20:21], v[26:27] op_sel_hi:[1,0,1]
	v_mov_b32_e32 v62, v79
	v_pk_fma_f32 v[26:27], v[28:29], v[22:23], v[26:27] op_sel_hi:[1,0,1]
	v_mov_b32_e32 v30, v80
	v_mov_b32_e32 v31, v64
	v_pk_fma_f32 v[26:27], v[62:63], v[24:25], v[26:27] op_sel_hi:[1,0,1]
	v_mov_b32_e32 v64, v81
	v_pk_fma_f32 v[26:27], v[30:31], v[34:35], v[26:27] op_sel_hi:[1,0,1]
	v_mov_b32_e32 v32, v106
	v_mov_b32_e32 v33, v91
	v_pk_fma_f32 v[26:27], v[64:65], v[36:37], v[26:27] op_sel_hi:[1,0,1]
	v_pk_mul_f32 v[32:33], v[32:33], v[18:19]
	v_pk_mov_b32 v[38:39], v[106:107], v[90:91] op_sel:[1,0]
	v_pk_add_f32 v[12:13], v[12:13], v[26:27]
	v_mov_b32_e32 v26, v108
	v_mov_b32_e32 v27, v92
	v_pk_fma_f32 v[32:33], v[38:39], v[18:19], v[32:33] op_sel:[0,1,0] op_sel_hi:[1,0,1]
	v_mov_b32_e32 v92, v109
	v_pk_fma_f32 v[26:27], v[26:27], v[0:1], v[32:33] op_sel_hi:[1,0,1]
	v_mov_b32_e32 v28, v110
	v_mov_b32_e32 v29, v94
	v_pk_fma_f32 v[26:27], v[92:93], v[20:21], v[26:27] op_sel_hi:[1,0,1]
	v_mov_b32_e32 v94, v111
	v_pk_fma_f32 v[26:27], v[28:29], v[22:23], v[26:27] op_sel_hi:[1,0,1]
	v_mov_b32_e32 v30, v112
	v_mov_b32_e32 v31, v96
	v_pk_fma_f32 v[26:27], v[94:95], v[24:25], v[26:27] op_sel_hi:[1,0,1]
	v_mov_b32_e32 v96, v113
	v_pk_fma_f32 v[26:27], v[30:31], v[34:35], v[26:27] op_sel_hi:[1,0,1]
	s_nop 0
	v_pk_fma_f32 v[26:27], v[96:97], v[36:37], v[26:27] op_sel_hi:[1,0,1]
	s_nop 0
	v_pk_add_f32 v[10:11], v[10:11], v[26:27]
	v_pk_mov_b32 v[26:27], v[126:127], v[142:143] op_sel:[1,0]
	v_mov_b32_e32 v127, v143
	v_pk_mul_f32 v[26:27], v[26:27], v[18:19] op_sel:[0,1] op_sel_hi:[1,0]
	s_nop 0
	v_pk_fma_f32 v[18:19], v[126:127], v[18:19], v[26:27]
	v_mov_b32_e32 v26, v128
	v_mov_b32_e32 v27, v144
	v_pk_fma_f32 v[18:19], v[26:27], v[0:1], v[18:19] op_sel_hi:[1,0,1]
	v_mov_b32_e32 v144, v129
	v_pk_fma_f32 v[18:19], v[144:145], v[20:21], v[18:19] op_sel_hi:[1,0,1]
	v_mov_b32_e32 v20, v122
	v_mov_b32_e32 v21, v138
	v_pk_fma_f32 v[18:19], v[20:21], v[22:23], v[18:19] op_sel_hi:[1,0,1]
	v_mov_b32_e32 v138, v123
	v_pk_fma_f32 v[18:19], v[138:139], v[24:25], v[18:19] op_sel_hi:[1,0,1]
	v_mov_b32_e32 v20, v124
	v_mov_b32_e32 v21, v140
	v_pk_fma_f32 v[18:19], v[20:21], v[34:35], v[18:19] op_sel_hi:[1,0,1]
	v_mov_b32_e32 v140, v125
	v_pk_fma_f32 v[18:19], v[140:141], v[36:37], v[18:19] op_sel_hi:[1,0,1]
	s_nop 0
	v_pk_add_f32 v[8:9], v[8:9], v[18:19]
	s_cbranch_scc0 .LBB0_132
; __device__ __forceinline__ void half_pair(float v, float& lo, float& hi) { auto rr = __builtin_amdgcn_permlane32_swap(__float_as_uint(v), __float_as_uint(v), false, false); lo = __uint_as_float(rr[0]); hi = __uint_as_float(rr[1]); }
; __global__ void __launch_bounds__(NWAVES * 64, 2) mega_fwd(Args args) {
;     ...
;                 for (int j = 0; j < 8; ++j) { float glo, ghi; half_pair(g8[j], glo, ghi); G16[j] = glo; G16[8 + j] = ghi; }
; #pragma unroll
;                 for (int n = 0; n < 16; ++n) G16[n] = (n < own) ? G16[n] : -INFINITY;
;                 unsigned selmask = 0u;
; #pragma unroll
;                 for (int k = 0; k < 3; ++k) { float best = -INFINITY; int bi = -1;
; #pragma unroll
;                     for (int n = 0; n < 16; ++n) if (G16[n] > best) { best = G16[n]; bi = n; }
;                     if (bi >= 0) selmask |= 1u << bi;
; #pragma unroll
;                     for (int n = 0; n < 16; ++n) G16[n] = (n == bi) ? -INFINITY : G16[n]; }
;                 bf16x8 qf[8]; load_qf<8>(qf, qrow, hi);
	s_lshl_b32 s7, s3, 9
	s_lshl_b32 s3, s3, 7
	s_and_b32 s46, s7, 0x3000
	s_add_i32 s47, s6, s84
	s_and_b32 s3, s3, 0x380
	s_add_i32 s7, s47, s46
	s_lshl_b32 s52, s3, 1
	v_mov_b32_e32 v0, v15
	s_cmp_lg_u32 s50, 0
	s_nop 0
	v_permlane32_swap_b32_e32 v15, v0
	v_mov_b32_e32 v6, v14
	v_mov_b32_e32 v181, 0xff800000
	s_cselect_b64 vcc, -1, 0
	s_cmp_gt_u32 s50, 1
	v_permlane32_swap_b32_e32 v14, v6
	v_mov_b32_e32 v7, v13
	v_cndmask_b32_e32 v15, v181, v15, vcc
	s_cselect_b64 vcc, -1, 0
	s_cmp_gt_u32 s50, 2
	v_permlane32_swap_b32_e32 v13, v7
	v_mov_b32_e32 v18, v12
	v_cndmask_b32_e32 v14, v181, v14, vcc
	s_cselect_b64 vcc, -1, 0
	s_cmp_gt_u32 s50, 3
	v_permlane32_swap_b32_e32 v12, v18
	v_mov_b32_e32 v19, v11
	v_cndmask_b32_e32 v13, v181, v13, vcc
	s_cselect_b64 vcc, -1, 0
	s_cmp_gt_u32 s50, 4
	v_permlane32_swap_b32_e32 v11, v19
	v_mov_b32_e32 v20, v10
	v_cndmask_b32_e32 v12, v181, v12, vcc
	s_cselect_b64 vcc, -1, 0
	s_cmp_gt_u32 s50, 5
	v_permlane32_swap_b32_e32 v10, v20
	v_mov_b32_e32 v21, v8
	v_cndmask_b32_e32 v11, v181, v11, vcc
	s_cselect_b64 vcc, -1, 0
	s_cmp_gt_u32 s50, 6
	v_permlane32_swap_b32_e32 v8, v21
	v_mov_b32_e32 v22, v9
	v_cndmask_b32_e32 v10, v181, v10, vcc
	s_cselect_b64 vcc, -1, 0
	s_cmp_gt_u32 s50, 7
	v_permlane32_swap_b32_e32 v9, v22
	v_cndmask_b32_e32 v8, v181, v8, vcc
	s_cselect_b64 vcc, -1, 0
	s_cmp_gt_u32 s50, 8
	v_cndmask_b32_e32 v9, v181, v9, vcc
	s_cselect_b64 vcc, -1, 0
	s_cmp_gt_u32 s50, 9
	v_cndmask_b32_e32 v0, v181, v0, vcc
	s_cselect_b64 vcc, -1, 0
	s_cmp_gt_u32 s50, 10
	v_cndmask_b32_e32 v6, v181, v6, vcc
	s_cselect_b64 vcc, -1, 0
	s_cmp_gt_u32 s50, 11
	v_cndmask_b32_e32 v7, v181, v7, vcc
	s_cselect_b64 vcc, -1, 0
	s_cmp_gt_u32 s50, 12
	v_cndmask_b32_e32 v18, v181, v18, vcc
	s_cselect_b64 vcc, -1, 0
	s_cmp_gt_u32 s50, 13
	v_cndmask_b32_e32 v19, v181, v19, vcc
	s_cselect_b64 vcc, -1, 0
	s_cmp_eq_u32 s50, 15
	v_cndmask_b32_e32 v20, v181, v20, vcc
	s_cselect_b64 vcc, -1, 0
	v_cndmask_b32_e32 v21, v181, v21, vcc
	v_cmp_nlg_f32_e32 vcc, s51, v15
	v_or_b32_e32 v178, s7, v3
	v_mov_b64_e32 v[4:5], s[72:73]
	v_cndmask_b32_e32 v22, v15, v181, vcc
	v_cndmask_b32_e64 v23, 0, -1, vcc
	v_cmp_gt_f32_e32 vcc, v14, v22
	s_movk_i32 s12, 0x2080
	v_mad_i64_i32 v[4:5], s[8:9], v178, s12, v[4:5]
	v_cndmask_b32_e32 v22, v22, v14, vcc
	v_cndmask_b32_e64 v23, v23, 1, vcc
	v_cmp_gt_f32_e32 vcc, v13, v22
	v_lshl_add_u64 v[4:5], v[4:5], 0, s[52:53]
	s_mov_b32 s7, 0x26200000
	v_cndmask_b32_e32 v22, v22, v13, vcc
	v_cndmask_b32_e64 v23, v23, 2, vcc
	v_cmp_gt_f32_e32 vcc, v12, v22
	v_add_u32_e32 v17, s77, v17
	s_add_u32 s52, s68, s52
	v_cndmask_b32_e32 v22, v22, v12, vcc
	v_cndmask_b32_e64 v23, v23, 3, vcc
	v_cmp_gt_f32_e32 vcc, v11, v22
	s_addc_u32 s65, s85, 0
	v_lshlrev_b32_e32 v223, 2, v16
	v_cndmask_b32_e32 v22, v22, v11, vcc
	v_cndmask_b32_e64 v23, v23, 4, vcc
	v_cmp_gt_f32_e32 vcc, v10, v22
	v_ashrrev_i32_e32 v179, 31, v178
	s_mov_b32 s64, 0
	v_cndmask_b32_e32 v22, v22, v10, vcc
	v_cndmask_b32_e64 v23, v23, 5, vcc
	v_cmp_gt_f32_e32 vcc, v8, v22
	v_mov_b32_e32 v227, 0
	s_mov_b32 s67, 0
	v_cndmask_b32_e32 v22, v22, v8, vcc
	v_cndmask_b32_e64 v23, v23, 6, vcc
	v_cmp_gt_f32_e32 vcc, v9, v22
	s_nop 1
	v_cndmask_b32_e32 v22, v22, v9, vcc
	v_cndmask_b32_e64 v23, v23, 7, vcc
	v_cmp_gt_f32_e32 vcc, v0, v22
	s_nop 1
	v_cndmask_b32_e32 v22, v22, v0, vcc
	v_cndmask_b32_e64 v23, v23, 8, vcc
	v_cmp_gt_f32_e32 vcc, v6, v22
	s_nop 1
	v_cndmask_b32_e32 v22, v22, v6, vcc
	v_cndmask_b32_e64 v23, v23, 9, vcc
	v_cmp_gt_f32_e32 vcc, v7, v22
	s_nop 1
	v_cndmask_b32_e32 v22, v22, v7, vcc
	v_cndmask_b32_e64 v23, v23, 10, vcc
	v_cmp_gt_f32_e32 vcc, v18, v22
	s_nop 1
	v_cndmask_b32_e32 v22, v22, v18, vcc
	v_cndmask_b32_e64 v23, v23, 11, vcc
	v_cmp_gt_f32_e32 vcc, v19, v22
	s_nop 1
	v_cndmask_b32_e32 v22, v22, v19, vcc
	v_cndmask_b32_e64 v23, v23, 12, vcc
	v_cmp_gt_f32_e32 vcc, v20, v22
	s_nop 1
	v_cndmask_b32_e32 v22, v22, v20, vcc
	v_cndmask_b32_e64 v23, v23, 13, vcc
	v_cmp_ngt_f32_e32 vcc, v21, v22
	s_nop 1
	v_cndmask_b32_e32 v22, 14, v23, vcc
	v_lshlrev_b32_e64 v23, v22, 1
	v_cmp_lt_i32_e32 vcc, -1, v22
	s_nop 1
	v_cndmask_b32_e32 v23, 0, v23, vcc
	v_cmp_ne_u32_e32 vcc, 0, v22
	s_nop 1
	v_cndmask_b32_e32 v15, v181, v15, vcc
	v_cmp_ne_u32_e32 vcc, 1, v22
	s_nop 1
	v_cndmask_b32_e32 v14, v181, v14, vcc
	v_cmp_ne_u32_e32 vcc, 2, v22
	s_nop 1
	v_cndmask_b32_e32 v13, v181, v13, vcc
	v_cmp_ne_u32_e32 vcc, 3, v22
	s_nop 1
	v_cndmask_b32_e32 v12, v181, v12, vcc
	v_cmp_ne_u32_e32 vcc, 4, v22
	s_nop 1
	v_cndmask_b32_e32 v11, v181, v11, vcc
	v_cmp_ne_u32_e32 vcc, 5, v22
	s_nop 1
	v_cndmask_b32_e32 v10, v181, v10, vcc
	v_cmp_ne_u32_e32 vcc, 6, v22
	s_nop 1
	v_cndmask_b32_e32 v8, v181, v8, vcc
	v_cmp_ne_u32_e32 vcc, 7, v22
	s_nop 1
	v_cndmask_b32_e32 v9, v181, v9, vcc
	v_cmp_ne_u32_e32 vcc, 8, v22
	s_nop 1
	v_cndmask_b32_e32 v24, v181, v0, vcc
	v_cmp_ne_u32_e32 vcc, 9, v22
	s_nop 1
	v_cndmask_b32_e32 v25, v181, v6, vcc
	v_cmp_ne_u32_e32 vcc, 10, v22
	s_nop 1
	v_cndmask_b32_e32 v26, v181, v7, vcc
	v_cmp_ne_u32_e32 vcc, 11, v22
	s_nop 1
	v_cndmask_b32_e32 v18, v181, v18, vcc
	v_cmp_ne_u32_e32 vcc, 12, v22
	s_nop 1
	v_cndmask_b32_e32 v19, v181, v19, vcc
	v_cmp_ne_u32_e32 vcc, 13, v22
	s_nop 1
	v_cndmask_b32_e32 v20, v181, v20, vcc
	v_cmp_ne_u32_e32 vcc, 14, v22
	s_nop 1
	v_cndmask_b32_e32 v21, v181, v21, vcc
	v_cmp_nlg_f32_e32 vcc, s51, v15
	s_nop 1
	v_cndmask_b32_e32 v0, v15, v181, vcc
	v_cndmask_b32_e64 v6, 0, -1, vcc
	v_cmp_gt_f32_e32 vcc, v14, v0
	s_nop 1
	v_cndmask_b32_e32 v0, v0, v14, vcc
	v_cndmask_b32_e64 v6, v6, 1, vcc
	v_cmp_gt_f32_e32 vcc, v13, v0
	s_nop 1
	v_cndmask_b32_e32 v0, v0, v13, vcc
	v_cndmask_b32_e64 v6, v6, 2, vcc
	v_cmp_gt_f32_e32 vcc, v12, v0
	s_nop 1
	v_cndmask_b32_e32 v0, v0, v12, vcc
	v_cndmask_b32_e64 v6, v6, 3, vcc
	v_cmp_gt_f32_e32 vcc, v11, v0
	s_nop 1
	v_cndmask_b32_e32 v22, v0, v11, vcc
	v_lshlrev_b32_e32 v0, 1, v2
	v_lshl_add_u64 v[4:5], v[4:5], 0, v[0:1]
	v_cndmask_b32_e64 v27, v6, 4, vcc
	v_lshl_add_u64 v[6:7], v[4:5], 0, s[62:63]
	v_add_co_u32_e32 v4, vcc, s7, v4
	s_mul_i32 s7, s3, 0x8080
	s_nop 0
	v_addc_co_u32_e32 v5, vcc, 0, v5, vcc
	global_load_dwordx4 v[82:85], v[4:5], off offset:1664
	global_load_dwordx4 v[86:89], v[6:7], off offset:32
	global_load_dwordx4 v[90:93], v[6:7], off offset:64
	global_load_dwordx4 v[94:97], v[6:7], off offset:96
	global_load_dwordx4 v[98:101], v[6:7], off offset:128
	global_load_dwordx4 v[102:105], v[6:7], off offset:160
	global_load_dwordx4 v[106:109], v[6:7], off offset:192
	global_load_dwordx4 v[110:113], v[6:7], off offset:224
	v_cmp_gt_f32_e32 vcc, v10, v22
	s_add_u32 s10, s92, s7
	s_addc_u32 s11, s93, 0
	v_cndmask_b32_e32 v0, v22, v10, vcc
	v_cndmask_b32_e64 v4, v27, 5, vcc
	v_cmp_gt_f32_e32 vcc, v8, v0
	s_addk_i32 s6, 0x100
	s_lshr_b32 s66, s6, 7
	v_cndmask_b32_e32 v0, v0, v8, vcc
	v_cndmask_b32_e64 v4, v4, 6, vcc
	v_cmp_gt_f32_e32 vcc, v9, v0
	s_mul_i32 s6, s46, 0x2080
	s_add_u32 s6, s52, s6
	v_cndmask_b32_e32 v0, v0, v9, vcc
	v_cndmask_b32_e64 v4, v4, 7, vcc
	v_cmp_gt_f32_e32 vcc, v24, v0
	s_addc_u32 s7, s65, 0
	s_waitcnt vmcnt(7)
; __global__ void __launch_bounds__(NWAVES * 64, 2) mega_fwd(Args args) {
;     ...
;                 for (int k = 0; k < 3; ++k) { float best = -INFINITY; int bi = -1;
; #pragma unroll
;                     for (int n = 0; n < 16; ++n) if (G16[n] > best) { best = G16[n]; bi = n; }
;                     if (bi >= 0) selmask |= 1u << bi;
; #pragma unroll
;                     for (int n = 0; n < 16; ++n) G16[n] = (n == bi) ? -INFINITY : G16[n]; }
	v_cndmask_b32_e32 v0, v0, v24, vcc
	v_cndmask_b32_e64 v4, v4, 8, vcc
	v_cmp_gt_f32_e32 vcc, v25, v0
	s_waitcnt vmcnt(6)
	s_waitcnt vmcnt(5)
	s_waitcnt vmcnt(4)
	s_waitcnt vmcnt(3)
	s_waitcnt vmcnt(2)
	v_cndmask_b32_e32 v0, v0, v25, vcc
	v_cndmask_b32_e64 v4, v4, 9, vcc
	v_cmp_gt_f32_e32 vcc, v26, v0
	s_waitcnt vmcnt(1)
	s_waitcnt vmcnt(0)
	v_cndmask_b32_e32 v0, v0, v26, vcc
	v_cndmask_b32_e64 v4, v4, 10, vcc
	v_cmp_gt_f32_e32 vcc, v18, v0
	s_nop 1
	v_cndmask_b32_e32 v0, v0, v18, vcc
	v_cndmask_b32_e64 v4, v4, 11, vcc
	v_cmp_gt_f32_e32 vcc, v19, v0
	s_nop 1
	v_cndmask_b32_e32 v0, v0, v19, vcc
	v_cndmask_b32_e64 v4, v4, 12, vcc
	v_cmp_gt_f32_e32 vcc, v20, v0
	s_nop 1
	v_cndmask_b32_e32 v0, v0, v20, vcc
	v_cndmask_b32_e64 v4, v4, 13, vcc
	v_cmp_ngt_f32_e32 vcc, v21, v0
	s_nop 1
	v_cndmask_b32_e32 v0, 14, v4, vcc
	v_lshlrev_b32_e64 v4, v0, 1
	v_cmp_lt_i32_e32 vcc, -1, v0
	s_nop 1
	v_cndmask_b32_e32 v6, 0, v4, vcc
	v_cmp_ne_u32_e32 vcc, 0, v0
	s_nop 1
	v_cndmask_b32_e32 v4, v181, v15, vcc
	v_cmp_ne_u32_e32 vcc, 1, v0
	s_nop 1
	v_cndmask_b32_e32 v7, v181, v14, vcc
	v_cmp_ne_u32_e32 vcc, 2, v0
	s_nop 1
	v_cndmask_b32_e32 v13, v181, v13, vcc
	v_cmp_ne_u32_e32 vcc, 3, v0
	s_nop 1
	v_cndmask_b32_e32 v12, v181, v12, vcc
	v_cmp_ne_u32_e32 vcc, 4, v0
	s_nop 1
	v_cndmask_b32_e32 v11, v181, v11, vcc
	v_cmp_ne_u32_e32 vcc, 5, v0
	s_nop 1
	v_cndmask_b32_e32 v10, v181, v10, vcc
	v_cmp_ne_u32_e32 vcc, 6, v0
	s_nop 1
	v_cndmask_b32_e32 v8, v181, v8, vcc
	v_cmp_ne_u32_e32 vcc, 7, v0
	s_nop 1
	v_cndmask_b32_e32 v9, v181, v9, vcc
	v_cmp_ne_u32_e32 vcc, 8, v0
	s_nop 1
	v_cndmask_b32_e32 v14, v181, v24, vcc
	v_cmp_ne_u32_e32 vcc, 9, v0
	s_nop 1
	v_cndmask_b32_e32 v15, v181, v25, vcc
	v_cmp_ne_u32_e32 vcc, 10, v0
	s_nop 1
	v_cndmask_b32_e32 v22, v181, v26, vcc
	v_cmp_ne_u32_e32 vcc, 11, v0
	s_nop 1
	v_cndmask_b32_e32 v18, v181, v18, vcc
	v_cmp_ne_u32_e32 vcc, 12, v0
	s_nop 1
	v_cndmask_b32_e32 v19, v181, v19, vcc
	v_cmp_ne_u32_e32 vcc, 13, v0
	s_nop 1
	v_cndmask_b32_e32 v20, v181, v20, vcc
	v_cmp_ne_u32_e32 vcc, 14, v0
	s_nop 1
	v_cndmask_b32_e32 v0, v181, v21, vcc
	v_cmp_nlg_f32_e32 vcc, s51, v4
	s_nop 1
	v_cndmask_b32_e32 v21, v4, v181, vcc
	v_ashrrev_i32_e32 v4, 31, v17
	v_lshrrev_b32_e32 v4, 28, v4
	v_add_u32_e32 v4, v17, v4
	v_ashrrev_i32_e32 v24, 4, v4
	v_and_b32_e32 v4, 0xffffff0, v4
	v_sub_u32_e32 v4, v17, v4
	v_lshlrev_b32_e32 v180, 4, v4
	v_mad_u64_u32 v[4:5], s[8:9], v24, s12, v[180:181]
	v_add_u32_e32 v5, 0x200, v17
	v_ashrrev_i32_e32 v25, 31, v5
	v_lshrrev_b32_e32 v25, 28, v25
	v_add_u32_e32 v25, v5, v25
	v_ashrrev_i32_e32 v26, 4, v25
	v_and_b32_e32 v25, 0xffffff0, v25
	v_sub_u32_e32 v5, v5, v25
	v_lshlrev_b32_e32 v182, 4, v5
	v_add_u32_e32 v5, 0x400, v17
	v_ashrrev_i32_e32 v25, 31, v5
	v_lshrrev_b32_e32 v25, 28, v25
	v_add_u32_e32 v25, v5, v25
	v_ashrrev_i32_e32 v27, 4, v25
	v_and_b32_e32 v25, 0xffffff0, v25
	v_sub_u32_e32 v5, v5, v25
	v_lshlrev_b32_e32 v186, 4, v5
	v_add_u32_e32 v5, 0x600, v17
	v_ashrrev_i32_e32 v17, 31, v5
	v_lshrrev_b32_e32 v17, 28, v17
	v_add_u32_e32 v17, v5, v17
	v_ashrrev_i32_e32 v25, 4, v17
	v_and_b32_e32 v17, 0xffffff0, v17
	v_sub_u32_e32 v5, v5, v17
	v_lshlrev_b32_e32 v190, 4, v5
	v_mad_u64_u32 v[184:185], s[8:9], v26, s12, v[182:183]
	v_mad_u64_u32 v[188:189], s[8:9], v27, s12, v[186:187]
	v_mad_u64_u32 v[192:193], s[8:9], v25, s12, v[190:191]
	global_load_dwordx4 v[114:117], v4, s[6:7]
	global_load_dwordx4 v[118:121], v184, s[6:7]
	global_load_dwordx4 v[122:125], v188, s[6:7]
	global_load_dwordx4 v[126:129], v192, s[6:7]
	s_lshl_b32 s6, s46, 1
	s_add_u32 s40, s10, s6
	s_movk_i32 s8, 0x6000
	s_addc_u32 s41, s11, 0
	v_mad_u64_u32 v[194:195], s[6:7], v24, s8, v[4:5]
	global_load_dwordx4 v[130:133], v194, s[40:41]
	v_mov_b32_e32 v185, v1
	v_mad_u64_u32 v[212:213], s[6:7], v26, s8, v[184:185]
	global_load_dwordx4 v[134:137], v212, s[40:41]
	v_mov_b32_e32 v189, v1
	v_mad_u64_u32 v[214:215], s[6:7], v27, s8, v[188:189]
	global_load_dwordx4 v[138:141], v214, s[40:41]
	v_mov_b32_e32 v193, v1
	v_mad_u64_u32 v[216:217], s[6:7], v25, s8, v[192:193]
	global_load_dwordx4 v[142:145], v216, s[40:41]
	v_cndmask_b32_e64 v5, 0, -1, vcc
	v_cmp_gt_f32_e32 vcc, v7, v21
	s_movk_i32 s6, 0x110
	v_mul_lo_u32 v187, v24, s6
	v_cndmask_b32_e32 v7, v21, v7, vcc
	v_cndmask_b32_e64 v5, v5, 1, vcc
	v_cmp_gt_f32_e32 vcc, v13, v7
	v_mul_lo_u32 v191, v26, s6
	v_mul_lo_u32 v218, v27, s6
	v_cndmask_b32_e32 v7, v7, v13, vcc
	v_cndmask_b32_e64 v5, v5, 2, vcc
	v_cmp_gt_f32_e32 vcc, v12, v7
	v_mul_lo_u32 v219, v25, s6
	v_subrev_u32_e32 v17, 25, v3
	v_cndmask_b32_e32 v7, v7, v12, vcc
	v_cndmask_b32_e64 v5, v5, 3, vcc
	v_cmp_gt_f32_e32 vcc, v11, v7
	s_movk_i32 s6, 0x108
	v_subrev_u32_e32 v12, 17, v3
	v_cndmask_b32_e32 v7, v7, v11, vcc
	v_cndmask_b32_e64 v5, v5, 4, vcc
	v_cmp_gt_f32_e32 vcc, v10, v7
	v_add_u32_e32 v11, -16, v3
	v_subrev_u32_e32 v13, 18, v3
	v_cndmask_b32_e32 v7, v7, v10, vcc
	v_cndmask_b32_e64 v5, v5, 5, vcc
	v_cmp_gt_f32_e32 vcc, v8, v7
	v_add_u32_e32 v10, -11, v3
	v_cmp_gt_i32_e64 s[34:35], v223, v17
	v_cndmask_b32_e32 v7, v7, v8, vcc
	v_cndmask_b32_e64 v5, v5, 6, vcc
	v_cmp_gt_f32_e32 vcc, v9, v7
	v_lshlrev_b32_e32 v8, 3, v24
	s_add_i32 s42, 0, 0x8800
	v_cndmask_b32_e32 v7, v7, v9, vcc
	v_cndmask_b32_e64 v5, v5, 7, vcc
	v_cmp_gt_f32_e32 vcc, v14, v7
	v_add_u32_e32 v9, -10, v3
	v_mov_b32_e32 v17, v1
	v_cndmask_b32_e32 v7, v7, v14, vcc
	v_cndmask_b32_e64 v5, v5, 8, vcc
	v_cmp_gt_f32_e32 vcc, v15, v7
	v_subrev_u32_e32 v14, 19, v3
	v_mul_lo_u32 v220, v24, s6
	v_cndmask_b32_e32 v7, v7, v15, vcc
	v_cndmask_b32_e64 v5, v5, 9, vcc
	v_cmp_gt_f32_e32 vcc, v22, v7
	v_subrev_u32_e32 v15, 24, v3
	v_mul_lo_u32 v221, v26, s6
	v_cndmask_b32_e32 v7, v7, v22, vcc
	v_cndmask_b32_e64 v5, v5, 10, vcc
	v_cmp_gt_f32_e32 vcc, v18, v7
	v_mul_lo_u32 v222, v27, s6
	v_mul_lo_u32 v224, v25, s6
	v_cndmask_b32_e32 v7, v7, v18, vcc
	v_cndmask_b32_e64 v5, v5, 11, vcc
	v_cmp_gt_f32_e32 vcc, v19, v7
	v_subrev_u32_e32 v18, 26, v3
	v_cmp_gt_i32_e64 s[6:7], v223, v3
	v_cndmask_b32_e32 v7, v7, v19, vcc
	v_cndmask_b32_e64 v5, v5, 12, vcc
	v_cmp_gt_f32_e32 vcc, v20, v7
	v_subrev_u32_e32 v19, 27, v3
	v_cmp_lt_i32_e64 s[8:9], v223, v3
	v_cndmask_b32_e32 v7, v7, v20, vcc
	v_cndmask_b32_e64 v5, v5, 13, vcc
	v_cmp_ngt_f32_e32 vcc, v0, v7
	v_add3_u32 v7, 0, v219, v190
	v_cmp_gt_i32_e64 s[18:19], v223, v9
	v_cndmask_b32_e32 v0, 14, v5, vcc
	v_lshlrev_b32_e64 v5, v0, 1
	v_cmp_lt_i32_e32 vcc, -1, v0
	v_cmp_gt_i32_e64 s[20:21], v223, v10
	v_cmp_gt_i32_e64 s[22:23], v223, v11
	v_cndmask_b32_e32 v0, 0, v5, vcc
	v_or3_b32 v183, v6, v23, v0
	s_lshl_b32 s100, 1, s50
	v_or_b32_e32 v183, s100, v183
	v_mov_b32_e32 v0, v4
	v_add3_u32 v4, 0, v187, v180
	s_waitcnt vmcnt(7)
; template <int NC>
; __device__ __forceinline__ void wg_attention128(LAS unsigned char* lds, const bf16* k1, int ldk1, const bf16* vt, int tok0, int nstages,
;         const bf16x8 (&qf)[NC], float sc, const CtlCausal& ctl, f32x16 (&o)[4], float& m, float& l, int tid, int r32, int hi) {
;     ...
; #pragma unroll
;     for (int c = 0; c < NC; ++c) asm volatile("" :: "v"(qf[c]));
;     WGB_LOAD(tok0); WGB_WRITE(0);
;     __syncthreads();
; __device__ __forceinline__ void zero_state(f32x16 (&o)[4], float& m, float& l) {
; #pragma unroll
;     for (int db = 0; db < 4; ++db)
; #pragma unroll
;         for (int i = 0; i < 16; ++i) o[db][i] = 0.f;
;     m = -INFINITY; l = 0.f;
	ds_write_b128 v4, v[114:117]
	v_sub_u32_e32 v4, v4, v8
	v_add3_u32 v5, 0, v191, v182
	v_add3_u32 v6, 0, v218, v186
	v_add_u32_e32 v4, 0x8800, v4
	s_waitcnt vmcnt(6)
	ds_write_b128 v5, v[118:121]
	s_waitcnt vmcnt(5)
	ds_write_b128 v6, v[122:125]
	s_waitcnt vmcnt(4)
	ds_write_b128 v7, v[126:129]
	s_waitcnt vmcnt(3)
	ds_write2_b64 v4, v[130:131], v[132:133] offset1:1
	v_lshlrev_b32_e32 v4, 3, v26
	v_sub_u32_e32 v4, v5, v4
	v_add_u32_e32 v4, 0x8800, v4
	s_waitcnt vmcnt(2)
	ds_write2_b64 v4, v[134:135], v[136:137] offset1:1
	v_lshlrev_b32_e32 v4, 3, v27
	v_sub_u32_e32 v4, v6, v4
	v_add_u32_e32 v4, 0x8800, v4
	s_waitcnt vmcnt(1)
	ds_write2_b64 v4, v[138:139], v[140:141] offset1:1
	v_lshlrev_b32_e32 v4, 3, v25
	v_sub_u32_e32 v4, v7, v4
	v_lshlrev_b32_e32 v5, 4, v16
	v_or_b32_e32 v16, 2, v223
	v_add_u32_e32 v4, 0x8800, v4
	v_cmp_gt_i32_e64 s[10:11], v16, v3
	v_or_b32_e32 v16, 3, v223
	s_waitcnt vmcnt(0)
	ds_write2_b64 v4, v[142:143], v[144:145] offset1:1
	v_mul_u32_u24_e32 v4, 0x110, v3
	v_mul_u32_u24_e32 v6, 0x108, v3
	v_add_u32_e32 v7, -8, v3
	v_add_u32_e32 v8, -9, v3
	v_cmp_gt_i32_e64 s[12:13], v16, v3
	v_mov_b32_e32 v16, v1
	v_cmp_gt_i32_e64 s[14:15], v223, v7
	v_cmp_gt_i32_e64 s[16:17], v223, v8
	v_cmp_gt_i32_e64 s[24:25], v223, v12
	v_cmp_gt_i32_e64 s[26:27], v223, v13
	v_cmp_gt_i32_e64 s[28:29], v223, v14
	v_cmp_gt_i32_e64 s[30:31], v223, v15
	v_cmp_gt_i32_e64 s[36:37], v223, v18
	v_cmp_gt_i32_e64 s[38:39], v223, v19
	v_add3_u32 v225, v6, v2, s42
	v_add3_u32 v226, v4, v5, 0
	v_mov_b32_e32 v2, v1
	v_mov_b32_e32 v3, v1
	v_mov_b32_e32 v4, v1
	v_mov_b32_e32 v5, v1
	v_mov_b32_e32 v6, v1
	v_mov_b32_e32 v7, v1
	v_mov_b32_e32 v8, v1
	v_mov_b32_e32 v9, v1
	v_mov_b32_e32 v10, v1
	v_mov_b32_e32 v11, v1
	v_mov_b32_e32 v12, v1
	v_mov_b32_e32 v13, v1
	v_mov_b32_e32 v14, v1
	v_mov_b32_e32 v15, v1
	v_mov_b64_e32 v[32:33], v[16:17]
	v_mov_b64_e32 v[48:49], v[16:17]
	v_mov_b64_e32 v[64:65], v[16:17]
	v_mov_b32_e32 v195, v1
	v_mov_b32_e32 v213, v1
	v_mov_b32_e32 v215, v1
	v_mov_b32_e32 v217, v1
	s_mov_b64 s[42:43], 0
	v_mov_b64_e32 v[30:31], v[14:15]
	v_mov_b64_e32 v[28:29], v[12:13]
	v_mov_b64_e32 v[26:27], v[10:11]
	v_mov_b64_e32 v[24:25], v[8:9]
	v_mov_b64_e32 v[22:23], v[6:7]
	v_mov_b64_e32 v[20:21], v[4:5]
	v_mov_b64_e32 v[18:19], v[2:3]
	v_mov_b64_e32 v[46:47], v[14:15]
	v_mov_b64_e32 v[44:45], v[12:13]
	v_mov_b64_e32 v[42:43], v[10:11]
	v_mov_b64_e32 v[40:41], v[8:9]
	v_mov_b64_e32 v[38:39], v[6:7]
	v_mov_b64_e32 v[36:37], v[4:5]
	v_mov_b64_e32 v[34:35], v[2:3]
	v_mov_b64_e32 v[62:63], v[14:15]
	v_mov_b64_e32 v[60:61], v[12:13]
	v_mov_b64_e32 v[58:59], v[10:11]
	v_mov_b64_e32 v[56:57], v[8:9]
	v_mov_b64_e32 v[54:55], v[6:7]
	v_mov_b64_e32 v[52:53], v[4:5]
	v_mov_b64_e32 v[50:51], v[2:3]
	s_waitcnt lgkmcnt(0)
	s_barrier

; __device__ __forceinline__ float half_max(float v) { float a, b; half_pair(v, a, b); return fmaxf(a, b); }
; __device__ __forceinline__ void att_softmax(f32x16& s, float sc, float& m, float& l, f32x16 (&o)[4], bf16x8& pf0, bf16x8& pf1) {
;     float mx = fmaxf(fmaxf(s[0], s[1]), fmaxf(s[2], s[3]));
; #pragma unroll
;     for (int i = 4; i < 16; i += 4) mx = fmaxf(mx, fmaxf(fmaxf(s[i], s[i + 1]), fmaxf(s[i + 2], s[i + 3])));
;     mx = half_max(mx);
;     const float mnew = fmaxf(m, mx * sc);
;     const float msafe = (mnew == -INFINITY) ? 0.f : mnew;
;     const float alpha = __builtin_amdgcn_exp2f(m - msafe);
;     m = mnew;
.LBB0_144:
	s_lshr_b32 s62, s88, 8
	s_cmp_eq_u32 s62, s50
	s_cselect_b64 s[60:61], -1, 0
	s_lshl_b32 s62, 1, s62
	v_and_b32_e32 v200, s62, v183
	v_cmp_ne_u32_e32 vcc, 0, v200
	s_nop 1
	v_cndmask_b32_e32 v245, v241, v66, vcc
	v_cndmask_b32_e32 v240, v241, v67, vcc
	v_cndmask_b32_e32 v238, v241, v68, vcc
	v_cndmask_b32_e32 v235, v241, v69, vcc
	v_max_f32_e32 v66, v240, v240
	v_max_f32_e32 v67, v245, v245
	v_cndmask_b32_e32 v232, v241, v72, vcc
	v_cndmask_b32_e32 v231, v241, v73, vcc
	v_cndmask_b32_e32 v230, v241, v74, vcc
	v_cndmask_b32_e32 v74, v241, v75, vcc
	v_max_f32_e32 v66, v67, v66
	v_max_f32_e32 v67, v235, v235
	v_max_f32_e32 v75, v238, v238
	v_cndmask_b32_e32 v73, v241, v76, vcc
	v_max_f32_e32 v67, v75, v67
	v_max_f32_e32 v75, v231, v231
	v_max_f32_e32 v76, v232, v232
	v_cndmask_b32_e32 v234, v241, v70, vcc
	v_cndmask_b32_e32 v233, v241, v71, vcc
	v_max_f32_e32 v75, v76, v75
	v_cndmask_b32_e32 v72, v241, v77, vcc
	v_max3_f32 v75, v234, v233, v75
	v_cndmask_b32_e32 v69, v241, v80, vcc
	v_cndmask_b32_e32 v68, v241, v81, vcc
	v_max3_f32 v66, v66, v67, v75
	v_max_f32_e32 v67, v72, v72
	v_max_f32_e32 v75, v73, v73
	v_max_f32_e32 v67, v75, v67
	v_max_f32_e32 v75, v68, v68
	v_max_f32_e32 v76, v69, v69
	v_cndmask_b32_e32 v71, v241, v78, vcc
	v_cndmask_b32_e32 v70, v241, v79, vcc
	v_max_f32_e32 v75, v76, v75
	v_max3_f32 v67, v230, v74, v67
	v_max3_f32 v75, v71, v70, v75
	v_max3_f32 v66, v66, v67, v75
	v_mov_b32_e32 v67, v66
	s_nop 1
	v_permlane32_swap_b32_e32 v66, v67
	v_max_f32_e32 v67, v67, v67
	v_max_f32_e32 v66, v66, v66
	v_max_f32_e32 v66, v66, v67
	v_mul_f32_e32 v66, 0x3e0293ee, v66
	v_max_f32_e32 v67, v181, v181
	v_max_f32_e32 v67, v67, v66
	v_cmp_neq_f32_e32 vcc, s51, v67
	s_nop 1
	v_cndmask_b32_e32 v75, 0, v67, vcc
	v_sub_f32_e32 v66, v181, v75
	v_exp_f32_e32 v66, v66
